# P0 weight transposition rewritten (register-only, double-buffered) with its bf16 stores lane-permuted so each lane quad writes 64 contiguous bytes; plus K-loop barrier shift and coalesced GEMM epilogu
# baseline (speedup 1.0000x reference)
; #define LAS __attribute__((address_space(3)))
; #define GAS1 __attribute__((address_space(1)))
; __device__ __forceinline__ void p0_transpose_item(const float* W, int K, int N, bf16* WT, int item, bool inproj, const float* gk, LAS float* scr, int lane) {
;     const int nblk = N / 64, kb = item / nblk, nb = item % nblk, k0 = 64 * kb, n0 = 64 * nb;
;     int sc = n0 + lane, cl = lane;
;     if (inproj && n0 < 3072) {
;         const int sec = n0 >> 10;
;         if (sec == 1) sc = n0 + 1024 + lane;
;         else { const int hb = (sec == 0 ? 1024 : 0) + (n0 & 1023 & ~127); sc = hb + ((n0 & 127) >> 1) + (lane & 31) + 64 * (lane >> 5); cl = 2 * (lane & 31) + (lane >> 5); }
;     }
;     const GAS1 float* src = (const GAS1 float*)(W + (size_t)k0 * N + sc);
; __global__ void __launch_bounds__(NWAVES * 64, 2) hybrid_fwd(Args a) {
;     ...
;     const int G = gridDim.x, bx = blockIdx.x, NGW = G * NWAVES;
;     const int wave_k = __builtin_amdgcn_readfirstlane((int)threadIdx.x >> 6);
;     ...
;     unsigned char* ws = a.ws;
;     ...
;     unsigned* barw = (unsigned*)(ws + WS_BAR);
;     if (bx == 0) for (int i = threadIdx.x; i < XCD_BAR_WORDS; i += NWAVES * 64) barw[i] = 0u;
;     volatile LAS unsigned* bst = (volatile LAS unsigned*)(lds + LDS_MAIN);
;     {
;         FRESH_IDS();
;         LAS float* scr = (LAS float*)(lds + wave * 16640);
;         constexpr int I_IN = (DM / 64) * (INW / 64), I_OUT = (DM / 64) * (DM / 64), I_UP = (DM / 64) * (DFF / 64), I_DN = (DFF / 64) * (DM / 64);
;         constexpr int PER_L = I_IN + I_OUT + I_UP + I_DN;
;         for (int it = gw; it < DEPTH * PER_L; it += NGW) {
;             const int l = it / PER_L; int r = it % PER_L;
;             if (r < I_IN) { p0_transpose_item(a.w_in + (size_t)l * DM * INW, DM, INW, Wi + (size_t)l * INW * DM, r, true, a.norm1_g + l * DM, scr, lane); continue; } r -= I_IN;
;             if (r < I_OUT) { p0_transpose_item(a.w_out + (size_t)l * DM * DM, DM, DM, Wo + (size_t)l * DM * DM, r, false, nullptr, scr, lane); continue; } r -= I_OUT;
;             if (r < I_UP) { p0_transpose_item(a.w_up + (size_t)l * DM * DFF, DM, DFF, Wu + (size_t)l * DFF * DM, r, false, a.norm2_g + l * DM, scr, lane); continue; } r -= I_UP;
;             p0_transpose_item(a.w_down + (size_t)l * DFF * DM, DFF, DM, Wd + (size_t)l * DM * DFF, r, false, nullptr, scr, lane);
.LBB0_8:
	v_writelane_b32 v252, s20, 5
	s_nop 1
	v_writelane_b32 v252, s21, 6
	v_writelane_b32 v252, s22, 7
	v_writelane_b32 v252, s23, 8
	v_writelane_b32 v252, s24, 9
	v_writelane_b32 v252, s25, 10
	v_writelane_b32 v252, s26, 11
	v_writelane_b32 v252, s27, 12
	v_writelane_b32 v252, s16, 13
	s_nop 1
	v_writelane_b32 v252, s17, 14
	v_writelane_b32 v252, s18, 15
	v_writelane_b32 v252, s19, 16
	s_load_dwordx16 s[8:23], s[0:1], 0x0
	s_waitcnt lgkmcnt(0)
	v_writelane_b32 v252, s8, 17
	s_nop 1
	v_writelane_b32 v252, s9, 18
	v_writelane_b32 v252, s10, 19
	v_writelane_b32 v252, s11, 20
	v_writelane_b32 v252, s12, 21
	v_writelane_b32 v252, s13, 22
	v_writelane_b32 v252, s14, 23
	v_writelane_b32 v252, s15, 24
	v_writelane_b32 v252, s16, 25
	v_writelane_b32 v252, s17, 26
	v_writelane_b32 v252, s18, 27
	v_writelane_b32 v252, s19, 28
	v_writelane_b32 v252, s20, 29
	v_writelane_b32 v252, s21, 30
	v_writelane_b32 v252, s22, 31
	v_writelane_b32 v252, s23, 32
	v_writelane_b32 v252, s6, 33
	s_lshl_b32 s0, s6, 3
	s_lshr_b32 s9, s4, 6
	v_writelane_b32 v252, s7, 34
	v_writelane_b32 v252, s0, 35
	v_writelane_b32 v252, s4, 36
	s_lshl_b32 s0, s94, 3
	v_writelane_b32 v252, s9, 37
	s_add_i32 s8, s9, s0
	s_cmpk_gt_i32 s8, 0x5bff
	v_writelane_b32 v252, s0, 38
	v_mbcnt_lo_u32_b32 v10, -1, 0
	v_mbcnt_hi_u32_b32 v10, -1, v10
	s_cbranch_scc1 .LBB0_36
	v_lshrrev_b32_e32 v20, 4, v10
	v_and_b32_e32 v21, 15, v10
	v_lshlrev_b32_e32 v22, 4, v20
	v_lshlrev_b32_e32 v23, 4, v21
	v_and_b32_e32 v29, 7, v21
	v_lshrrev_b32_e32 v34, 3, v21
	v_lshlrev_b32_e32 v24, 4, v29
	v_lshl_add_u32 v24, v34, 8, v24
	v_lshlrev_b32_e32 v25, 2, v21
	v_lshl_add_u32 v26, v29, 3, v34
	v_lshlrev_b32_e32 v27, 3, v20
	v_lshlrev_b32_e32 v28, 5, v20
	v_and_b32_e32 v38, 3, v10
	v_lshrrev_b32_e32 v39, 2, v10
	v_lshl_add_u32 v37, v38, 4, v39
	v_lshlrev_b32_e32 v37, 2, v37
	v_lshlrev_b32_e32 v22, 4, v38
	v_lshlrev_b32_e32 v25, 2, v39
	v_and_b32_e32 v38, 7, v39
	v_lshrrev_b32_e32 v39, 3, v39
	v_lshl_add_u32 v26, v38, 3, v39
	v_readlane_b32 s11, v252, 35
	s_mov_b32 s10, s8
	s_cmp_ge_u32 s10, 11776
	s_cselect_b32 s0, 1, 0
	s_cselect_b32 s1, 11776, 0
	s_sub_u32 s1, s10, s1
	s_lshl_b32 s7, s0, 13
	s_mov_b32 s26, 0
	s_cmp_lt_u32 s1, 2560
	s_cbranch_scc1 .Lp0_in_A0
	s_cmp_lt_u32 s1, 3584
	s_cbranch_scc1 .Lp0_out_A0
	s_cmp_lt_u32 s1, 7680
	s_cbranch_scc1 .Lp0_up_A0
	s_sub_u32 s1, s1, 7680
	s_and_b32 s4, s1, 7
	s_lshr_b32 s5, s1, 3
	s_lshr_b32 s2, s5, 2
	s_and_b32 s3, s5, 3
	s_lshl_b32 s2, s2, 0
	s_lshl_b32 s3, s3, 3
	s_lshr_b32 s5, s4, 3
	s_and_b32 s4, s4, 7
	s_add_u32 s2, s2, s5
	s_add_u32 s3, s3, s4
	v_readlane_b32 s4, v252, 9
	v_readlane_b32 s5, v252, 10
	s_mul_i32 s6, s0, 0x4000000
	s_mul_i32 s12, s2, 0x80000
	s_lshl_b32 s13, s3, 8
	s_add_u32 s12, s12, s13
	s_add_u32 s12, s12, s6
	s_add_u32 s16, s4, s12
	s_addc_u32 s17, s5, 0
	s_mov_b32 s18, 0x2000
	s_mov_b32 s19, 0x32000
	s_mul_i32 s6, s0, 0x2000000
	s_add_u32 s6, s6, 0x7800000
	s_lshl_b32 s12, s3, 20
	s_lshl_b32 s13, s2, 7
	s_add_u32 s12, s12, s13
	s_add_u32 s12, s12, s6
	s_mov_b32 s27, 0x4000
	s_mov_b32 s22, 0x4000
	s_mov_b32 s23, 0
	v_readlane_b32 s24, v252, 19
	v_readlane_b32 s25, v252, 20
	s_branch .Lp0_dec_done_A0

; #define LAS __attribute__((address_space(3)))
; #define GAS1 __attribute__((address_space(1)))
; #define LDS_WAIT() asm volatile("s_waitcnt lgkmcnt(0)" ::: "memory")
; __device__ __forceinline__ unsigned pk2(float lo, float hi) { return pg8::cvt_pk_bf16(lo, hi); }
; __device__ __forceinline__ void p0_transpose_item(const float* W, int K, int N, bf16* WT, int item, bool inproj, const float* gk, LAS float* scr, int lane) {
;     ...
;     for (int j = 0; j < 8; ++j) { const int n = (lane & 7) + 8 * j; const LAS float* s = scr + (8 * c) * 65 + n;
;         v4u o; o.x = pk2(s[0 * 65] * g0.x, s[1 * 65] * g0.y); o.y = pk2(s[2 * 65] * g0.z, s[3 * 65] * g0.w); o.z = pk2(s[4 * 65] * g1.x, s[5 * 65] * g1.y); o.w = pk2(s[6 * 65] * g1.z, s[7 * 65] * g1.w);
;         *(GAS1 v4u*)(WT + (size_t)(n0 + n) * K + k0 + 8 * c) = o; }
;     LDS_WAIT(); asm volatile("" ::: "memory");
.Lp0_nog_A0:
	v_cvt_pk_bf16_f32 v208, v40, v44
	v_cvt_pk_bf16_f32 v209, v48, v52
	v_cvt_pk_bf16_f32 v210, v56, v60
	v_cvt_pk_bf16_f32 v211, v64, v68
	v_cvt_pk_bf16_f32 v212, v72, v76
	v_cvt_pk_bf16_f32 v213, v80, v84
	v_cvt_pk_bf16_f32 v214, v88, v92
	v_cvt_pk_bf16_f32 v215, v96, v100
	v_cvt_pk_bf16_f32 v216, v41, v45
	v_cvt_pk_bf16_f32 v217, v49, v53
	v_cvt_pk_bf16_f32 v218, v57, v61
	v_cvt_pk_bf16_f32 v219, v65, v69
	v_cvt_pk_bf16_f32 v220, v73, v77
	v_cvt_pk_bf16_f32 v221, v81, v85
	v_cvt_pk_bf16_f32 v222, v89, v93
	v_cvt_pk_bf16_f32 v223, v97, v101
	v_cvt_pk_bf16_f32 v224, v42, v46
	v_cvt_pk_bf16_f32 v225, v50, v54
	v_cvt_pk_bf16_f32 v226, v58, v62
	v_cvt_pk_bf16_f32 v227, v66, v70
	v_cvt_pk_bf16_f32 v228, v74, v78
	v_cvt_pk_bf16_f32 v229, v82, v86
	v_cvt_pk_bf16_f32 v230, v90, v94
	v_cvt_pk_bf16_f32 v231, v98, v102
	v_cvt_pk_bf16_f32 v232, v43, v47
	v_cvt_pk_bf16_f32 v233, v51, v55
	v_cvt_pk_bf16_f32 v234, v59, v63
	v_cvt_pk_bf16_f32 v235, v67, v71
	v_cvt_pk_bf16_f32 v236, v75, v79
	v_cvt_pk_bf16_f32 v237, v83, v87
	v_cvt_pk_bf16_f32 v238, v91, v95
	v_cvt_pk_bf16_f32 v239, v99, v103
	ds_bpermute_b32 v208, v37, v208
	ds_bpermute_b32 v209, v37, v209
	ds_bpermute_b32 v210, v37, v210
	ds_bpermute_b32 v211, v37, v211
	ds_bpermute_b32 v212, v37, v212
	ds_bpermute_b32 v213, v37, v213
	ds_bpermute_b32 v214, v37, v214
	ds_bpermute_b32 v215, v37, v215
	ds_bpermute_b32 v216, v37, v216
	ds_bpermute_b32 v217, v37, v217
	ds_bpermute_b32 v218, v37, v218
	ds_bpermute_b32 v219, v37, v219
	ds_bpermute_b32 v220, v37, v220
	ds_bpermute_b32 v221, v37, v221
	ds_bpermute_b32 v222, v37, v222
	ds_bpermute_b32 v223, v37, v223
	ds_bpermute_b32 v224, v37, v224
	ds_bpermute_b32 v225, v37, v225
	ds_bpermute_b32 v226, v37, v226
	ds_bpermute_b32 v227, v37, v227
	ds_bpermute_b32 v228, v37, v228
	ds_bpermute_b32 v229, v37, v229
	ds_bpermute_b32 v230, v37, v230
	ds_bpermute_b32 v231, v37, v231
	ds_bpermute_b32 v232, v37, v232
	ds_bpermute_b32 v233, v37, v233
	ds_bpermute_b32 v234, v37, v234
	ds_bpermute_b32 v235, v37, v235
	ds_bpermute_b32 v236, v37, v236
	ds_bpermute_b32 v237, v37, v237
	ds_bpermute_b32 v238, v37, v238
	ds_bpermute_b32 v239, v37, v239
	s_waitcnt lgkmcnt(0)
	global_store_dwordx4 v31, v[208:211], s[20:21]
	global_store_dwordx4 v31, v[212:215], s[20:21] offset:64
	s_add_u32 s20, s20, s22
	s_addc_u32 s21, s21, 0
	global_store_dwordx4 v31, v[216:219], s[20:21]
	global_store_dwordx4 v31, v[220:223], s[20:21] offset:64
	s_add_u32 s20, s20, s22
	s_addc_u32 s21, s21, 0
	global_store_dwordx4 v31, v[224:227], s[20:21]
	global_store_dwordx4 v31, v[228:231], s[20:21] offset:64
	s_add_u32 s20, s20, s22
	s_addc_u32 s21, s21, 0
	global_store_dwordx4 v31, v[232:235], s[20:21]
	global_store_dwordx4 v31, v[236:239], s[20:21] offset:64
	s_cmp_eq_u32 s59, 0
	s_cbranch_scc1 .Lp0_done

; #define LAS __attribute__((address_space(3)))
; #define GAS1 __attribute__((address_space(1)))
; __device__ __forceinline__ unsigned pk2(float lo, float hi) { return pg8::cvt_pk_bf16(lo, hi); }
; __device__ __forceinline__ void p0_transpose_item(const float* W, int K, int N, bf16* WT, int item, bool inproj, const float* gk, LAS float* scr, int lane) {
;     ...
;     for (int j = 0; j < 8; ++j) { const int n = (lane & 7) + 8 * j; const LAS float* s = scr + (8 * c) * 65 + n;
;         v4u o; o.x = pk2(s[0 * 65] * g0.x, s[1 * 65] * g0.y); o.y = pk2(s[2 * 65] * g0.z, s[3 * 65] * g0.w); o.z = pk2(s[4 * 65] * g1.x, s[5 * 65] * g1.y); o.w = pk2(s[6 * 65] * g1.z, s[7 * 65] * g1.w);
;         *(GAS1 v4u*)(WT + (size_t)(n0 + n) * K + k0 + 8 * c) = o; }
; __global__ void __launch_bounds__(NWAVES * 64, 2) hybrid_fwd(Args a) {
;     ...
;         for (int it = gw; it < DEPTH * PER_L; it += NGW) {
;             const int l = it / PER_L; int r = it % PER_L;
;             if (r < I_IN) { p0_transpose_item(a.w_in + (size_t)l * DM * INW, DM, INW, Wi + (size_t)l * INW * DM, r, true, a.norm1_g + l * DM, scr, lane); continue; } r -= I_IN;
;             if (r < I_OUT) { p0_transpose_item(a.w_out + (size_t)l * DM * DM, DM, DM, Wo + (size_t)l * DM * DM, r, false, nullptr, scr, lane); continue; } r -= I_OUT;
;             if (r < I_UP) { p0_transpose_item(a.w_up + (size_t)l * DM * DFF, DM, DFF, Wu + (size_t)l * DFF * DM, r, false, a.norm2_g + l * DM, scr, lane); continue; } r -= I_UP;
;             p0_transpose_item(a.w_down + (size_t)l * DFF * DM, DFF, DM, Wd + (size_t)l * DM * DFF, r, false, nullptr, scr, lane);
.Lp0_nog_B1:
	v_cvt_pk_bf16_f32 v208, v120, v124
	v_cvt_pk_bf16_f32 v209, v128, v132
	v_cvt_pk_bf16_f32 v210, v136, v140
	v_cvt_pk_bf16_f32 v211, v144, v148
	v_cvt_pk_bf16_f32 v212, v152, v156
	v_cvt_pk_bf16_f32 v213, v160, v164
	v_cvt_pk_bf16_f32 v214, v168, v172
	v_cvt_pk_bf16_f32 v215, v176, v180
	v_cvt_pk_bf16_f32 v216, v121, v125
	v_cvt_pk_bf16_f32 v217, v129, v133
	v_cvt_pk_bf16_f32 v218, v137, v141
	v_cvt_pk_bf16_f32 v219, v145, v149
	v_cvt_pk_bf16_f32 v220, v153, v157
	v_cvt_pk_bf16_f32 v221, v161, v165
	v_cvt_pk_bf16_f32 v222, v169, v173
	v_cvt_pk_bf16_f32 v223, v177, v181
	v_cvt_pk_bf16_f32 v224, v122, v126
	v_cvt_pk_bf16_f32 v225, v130, v134
	v_cvt_pk_bf16_f32 v226, v138, v142
	v_cvt_pk_bf16_f32 v227, v146, v150
	v_cvt_pk_bf16_f32 v228, v154, v158
	v_cvt_pk_bf16_f32 v229, v162, v166
	v_cvt_pk_bf16_f32 v230, v170, v174
	v_cvt_pk_bf16_f32 v231, v178, v182
	v_cvt_pk_bf16_f32 v232, v123, v127
	v_cvt_pk_bf16_f32 v233, v131, v135
	v_cvt_pk_bf16_f32 v234, v139, v143
	v_cvt_pk_bf16_f32 v235, v147, v151
	v_cvt_pk_bf16_f32 v236, v155, v159
	v_cvt_pk_bf16_f32 v237, v163, v167
	v_cvt_pk_bf16_f32 v238, v171, v175
	v_cvt_pk_bf16_f32 v239, v179, v183
	ds_bpermute_b32 v208, v37, v208
	ds_bpermute_b32 v209, v37, v209
	ds_bpermute_b32 v210, v37, v210
	ds_bpermute_b32 v211, v37, v211
	ds_bpermute_b32 v212, v37, v212
	ds_bpermute_b32 v213, v37, v213
	ds_bpermute_b32 v214, v37, v214
	ds_bpermute_b32 v215, v37, v215
	ds_bpermute_b32 v216, v37, v216
	ds_bpermute_b32 v217, v37, v217
	ds_bpermute_b32 v218, v37, v218
	ds_bpermute_b32 v219, v37, v219
	ds_bpermute_b32 v220, v37, v220
	ds_bpermute_b32 v221, v37, v221
	ds_bpermute_b32 v222, v37, v222
	ds_bpermute_b32 v223, v37, v223
	ds_bpermute_b32 v224, v37, v224
	ds_bpermute_b32 v225, v37, v225
	ds_bpermute_b32 v226, v37, v226
	ds_bpermute_b32 v227, v37, v227
	ds_bpermute_b32 v228, v37, v228
	ds_bpermute_b32 v229, v37, v229
	ds_bpermute_b32 v230, v37, v230
	ds_bpermute_b32 v231, v37, v231
	ds_bpermute_b32 v232, v37, v232
	ds_bpermute_b32 v233, v37, v233
	ds_bpermute_b32 v234, v37, v234
	ds_bpermute_b32 v235, v37, v235
	ds_bpermute_b32 v236, v37, v236
	ds_bpermute_b32 v237, v37, v237
	ds_bpermute_b32 v238, v37, v238
	ds_bpermute_b32 v239, v37, v239
	s_waitcnt lgkmcnt(0)
	global_store_dwordx4 v33, v[208:211], s[44:45]
	global_store_dwordx4 v33, v[212:215], s[44:45] offset:64
	s_add_u32 s44, s44, s46
	s_addc_u32 s45, s45, 0
	global_store_dwordx4 v33, v[216:219], s[44:45]
	global_store_dwordx4 v33, v[220:223], s[44:45] offset:64
	s_add_u32 s44, s44, s46
	s_addc_u32 s45, s45, 0
	global_store_dwordx4 v33, v[224:227], s[44:45]
	global_store_dwordx4 v33, v[228:231], s[44:45] offset:64
	s_add_u32 s44, s44, s46
	s_addc_u32 s45, s45, 0
	global_store_dwordx4 v33, v[232:235], s[44:45]
	global_store_dwordx4 v33, v[236:239], s[44:45] offset:64
	s_cmp_eq_u32 s59, 0
	s_cbranch_scc1 .Lp0_done
	s_add_u32 s10, s10, s11
	s_cmp_lt_u32 s10, 23552
	s_cselect_b32 s59, 1, 0
	s_cbranch_scc0 .Lp0_last_b
	s_cmp_ge_u32 s10, 11776
	s_cselect_b32 s0, 1, 0
	s_cselect_b32 s1, 11776, 0
	s_sub_u32 s1, s10, s1
	s_lshl_b32 s7, s0, 13
	s_mov_b32 s50, 0
	s_cmp_lt_u32 s1, 2560
	s_cbranch_scc1 .Lp0_in_B3
	s_cmp_lt_u32 s1, 3584
	s_cbranch_scc1 .Lp0_out_B3
	s_cmp_lt_u32 s1, 7680
	s_cbranch_scc1 .Lp0_up_B3
	s_sub_u32 s1, s1, 7680
	s_and_b32 s4, s1, 7
	s_lshr_b32 s5, s1, 3
	s_lshr_b32 s2, s5, 2
	s_and_b32 s3, s5, 3
	s_lshl_b32 s2, s2, 0
	s_lshl_b32 s3, s3, 3
	s_lshr_b32 s5, s4, 3
	s_and_b32 s4, s4, 7
	s_add_u32 s2, s2, s5
	s_add_u32 s3, s3, s4
	v_readlane_b32 s4, v252, 9
	v_readlane_b32 s5, v252, 10
	s_mul_i32 s6, s0, 0x4000000
	s_mul_i32 s12, s2, 0x80000
	s_lshl_b32 s13, s3, 8
	s_add_u32 s12, s12, s13
	s_add_u32 s12, s12, s6
	s_add_u32 s40, s4, s12
	s_addc_u32 s41, s5, 0
	s_mov_b32 s42, 0x2000
	s_mov_b32 s43, 0x32000
	s_mul_i32 s6, s0, 0x2000000
	s_add_u32 s6, s6, 0x7800000
	s_lshl_b32 s12, s3, 20
	s_lshl_b32 s13, s2, 7
	s_add_u32 s12, s12, s13
	s_add_u32 s12, s12, s6
	s_mov_b32 s51, 0x4000
	s_mov_b32 s46, 0x4000
	s_mov_b32 s47, 0
	v_readlane_b32 s48, v252, 19
	v_readlane_b32 s49, v252, 20
	s_branch .Lp0_dec_done_B3

; #define LAS __attribute__((address_space(3)))
; #define GAS1 __attribute__((address_space(1)))
; __device__ __forceinline__ unsigned pk2(float lo, float hi) { return pg8::cvt_pk_bf16(lo, hi); }
; __device__ __forceinline__ void p0_transpose_item(const float* W, int K, int N, bf16* WT, int item, bool inproj, const float* gk, LAS float* scr, int lane) {
;     ...
;     for (int j = 0; j < 8; ++j) { const int n = (lane & 7) + 8 * j; const LAS float* s = scr + (8 * c) * 65 + n;
;         v4u o; o.x = pk2(s[0 * 65] * g0.x, s[1 * 65] * g0.y); o.y = pk2(s[2 * 65] * g0.z, s[3 * 65] * g0.w); o.z = pk2(s[4 * 65] * g1.x, s[5 * 65] * g1.y); o.w = pk2(s[6 * 65] * g1.z, s[7 * 65] * g1.w);
;         *(GAS1 v4u*)(WT + (size_t)(n0 + n) * K + k0 + 8 * c) = o; }
; __global__ void __launch_bounds__(NWAVES * 64, 2) hybrid_fwd(Args a) {
;     ...
;         for (int it = gw; it < DEPTH * PER_L; it += NGW) {
.Lp0_nog_A2:
	v_cvt_pk_bf16_f32 v208, v40, v44
	v_cvt_pk_bf16_f32 v209, v48, v52
	v_cvt_pk_bf16_f32 v210, v56, v60
	v_cvt_pk_bf16_f32 v211, v64, v68
	v_cvt_pk_bf16_f32 v212, v72, v76
	v_cvt_pk_bf16_f32 v213, v80, v84
	v_cvt_pk_bf16_f32 v214, v88, v92
	v_cvt_pk_bf16_f32 v215, v96, v100
	v_cvt_pk_bf16_f32 v216, v41, v45
	v_cvt_pk_bf16_f32 v217, v49, v53
	v_cvt_pk_bf16_f32 v218, v57, v61
	v_cvt_pk_bf16_f32 v219, v65, v69
	v_cvt_pk_bf16_f32 v220, v73, v77
	v_cvt_pk_bf16_f32 v221, v81, v85
	v_cvt_pk_bf16_f32 v222, v89, v93
	v_cvt_pk_bf16_f32 v223, v97, v101
	v_cvt_pk_bf16_f32 v224, v42, v46
	v_cvt_pk_bf16_f32 v225, v50, v54
	v_cvt_pk_bf16_f32 v226, v58, v62
	v_cvt_pk_bf16_f32 v227, v66, v70
	v_cvt_pk_bf16_f32 v228, v74, v78
	v_cvt_pk_bf16_f32 v229, v82, v86
	v_cvt_pk_bf16_f32 v230, v90, v94
	v_cvt_pk_bf16_f32 v231, v98, v102
	v_cvt_pk_bf16_f32 v232, v43, v47
	v_cvt_pk_bf16_f32 v233, v51, v55
	v_cvt_pk_bf16_f32 v234, v59, v63
	v_cvt_pk_bf16_f32 v235, v67, v71
	v_cvt_pk_bf16_f32 v236, v75, v79
	v_cvt_pk_bf16_f32 v237, v83, v87
	v_cvt_pk_bf16_f32 v238, v91, v95
	v_cvt_pk_bf16_f32 v239, v99, v103
	ds_bpermute_b32 v208, v37, v208
	ds_bpermute_b32 v209, v37, v209
	ds_bpermute_b32 v210, v37, v210
	ds_bpermute_b32 v211, v37, v211
	ds_bpermute_b32 v212, v37, v212
	ds_bpermute_b32 v213, v37, v213
	ds_bpermute_b32 v214, v37, v214
	ds_bpermute_b32 v215, v37, v215
	ds_bpermute_b32 v216, v37, v216
	ds_bpermute_b32 v217, v37, v217
	ds_bpermute_b32 v218, v37, v218
	ds_bpermute_b32 v219, v37, v219
	ds_bpermute_b32 v220, v37, v220
	ds_bpermute_b32 v221, v37, v221
	ds_bpermute_b32 v222, v37, v222
	ds_bpermute_b32 v223, v37, v223
	ds_bpermute_b32 v224, v37, v224
	ds_bpermute_b32 v225, v37, v225
	ds_bpermute_b32 v226, v37, v226
	ds_bpermute_b32 v227, v37, v227
	ds_bpermute_b32 v228, v37, v228
	ds_bpermute_b32 v229, v37, v229
	ds_bpermute_b32 v230, v37, v230
	ds_bpermute_b32 v231, v37, v231
	ds_bpermute_b32 v232, v37, v232
	ds_bpermute_b32 v233, v37, v233
	ds_bpermute_b32 v234, v37, v234
	ds_bpermute_b32 v235, v37, v235
	ds_bpermute_b32 v236, v37, v236
	ds_bpermute_b32 v237, v37, v237
	ds_bpermute_b32 v238, v37, v238
	ds_bpermute_b32 v239, v37, v239
	s_waitcnt lgkmcnt(0)
	global_store_dwordx4 v31, v[208:211], s[20:21]
	global_store_dwordx4 v31, v[212:215], s[20:21] offset:64
	s_add_u32 s20, s20, s22
	s_addc_u32 s21, s21, 0
	global_store_dwordx4 v31, v[216:219], s[20:21]
	global_store_dwordx4 v31, v[220:223], s[20:21] offset:64
	s_add_u32 s20, s20, s22
	s_addc_u32 s21, s21, 0
	global_store_dwordx4 v31, v[224:227], s[20:21]
	global_store_dwordx4 v31, v[228:231], s[20:21] offset:64
	s_add_u32 s20, s20, s22
	s_addc_u32 s21, s21, 0
	global_store_dwordx4 v31, v[232:235], s[20:21]
	global_store_dwordx4 v31, v[236:239], s[20:21] offset:64
	s_cmp_eq_u32 s59, 0
	s_cbranch_scc0 .Lp0_loop
